# attention next-supertile K/V prefetch distance tuned: 3/3/2/0 loads over the four sub-tile iterations instead of 2/2/2/2
# baseline (speedup 1.0000x reference)
.LBB0_158:
	s_cmp_eq_u32 s2, s4
	s_cbranch_scc1 .Lat_done
	s_cmpk_eq_i32 s14, 0
	s_cbranch_scc0 .Lat_1
	buffer_load_dwordx4 v[106:109], v106, s[76:79], 0 offen sc1
	buffer_load_dwordx4 v[110:113], v110, s[76:79], 0 offen sc1
	buffer_load_dwordx4 v[114:117], v114, s[76:79], 0 offen sc1
	s_branch .Lat_done
.Lat_1:
	s_cmpk_eq_i32 s14, 0xffc0
	s_cbranch_scc0 .Lat_2
	buffer_load_dwordx4 v[118:121], v118, s[76:79], 0 offen sc1
	buffer_load_dwordx4 v[122:125], v122, s[76:79], 0 offen sc1
	buffer_load_dwordx4 v[126:129], v126, s[76:79], 0 offen sc1
	s_branch .Lat_done
.Lat_2:
	s_cmpk_eq_i32 s14, 0xff80
	s_cbranch_scc0 .Lat_done
	buffer_load_dwordx4 v[130:133], v130, s[76:79], 0 offen sc1
	buffer_load_dwordx4 v[134:137], v134, s[76:79], 0 offen sc1
